# nt cache hint on the once-read K-slice partial tiles summed by P9's context rows
# baseline (speedup 1.0000x reference)
; #define GAS __attribute__((address_space(1)))
;     ...
;         if (nparts > 0 && m >= ML) {
;             for (int p = 0; p < nparts; p += 4) {
;                 const GAS f32x4* pr = (const GAS f32x4*)(parts + (size_t)p * (512 * 1024) + (size_t)(m - ML) * DM) + F.lane;
;                 f32x4 w[4][4];
; #pragma unroll
;                 for (int q = 0; q < 4; ++q)
; #pragma unroll
;                     for (int j = 0; j < 4; ++j) w[q][j] = pr[(size_t)q * (512 * 1024 / 4) + 64 * j];
; #pragma unroll
;                 for (int j = 0; j < 4; ++j) v[j] += (w[0][j] + w[1][j]) + (w[2][j] + w[3][j]); }
;             GAS f32x4* cr = (GAS f32x4*)((float*)(F.ws + WS_CTXRES) + (size_t)(m - ML) * DM) + F.lane;
; #pragma unroll
;             for (int j = 0; j < 4; ++j) cr[64 * j] = v[j];
.LBB0_166:
	v_readlane_b32 s14, v243, 9
	v_readlane_b32 s15, v243, 10
	s_add_i32 s14, s0, 0xffffc000
	s_mov_b32 s1, s15
	s_lshl_b64 s[14:15], s[14:15], 12
	s_add_u32 s18, s16, s14
	v_writelane_b32 v243, s0, 9
	s_addc_u32 s19, s17, s15
	v_lshl_add_u64 v[66:67], s[18:19], 0, v[0:1]
	v_writelane_b32 v243, s1, 10
	s_mov_b32 s1, 0x200000
	v_add_co_u32_e32 v62, vcc, s1, v66
	s_mov_b32 s1, 0x400000
	s_nop 0
	v_addc_co_u32_e32 v63, vcc, 0, v67, vcc
	v_add_co_u32_e32 v80, vcc, s1, v66
	s_mov_b32 s1, 0x600000
	s_nop 0
	v_addc_co_u32_e32 v81, vcc, 0, v67, vcc
	global_load_dwordx4 v[34:37], v0, s[18:19] nt
	global_load_dwordx4 v[38:41], v0, s[18:19] offset:1024 nt
	global_load_dwordx4 v[42:45], v0, s[18:19] offset:2048 nt
	global_load_dwordx4 v[58:61], v0, s[18:19] offset:3072 nt
	global_load_dwordx4 v[46:49], v[62:63], off nt
	global_load_dwordx4 v[50:53], v[62:63], off offset:1024 nt
	global_load_dwordx4 v[54:57], v[62:63], off offset:2048 nt
	s_nop 0
	global_load_dwordx4 v[62:65], v[62:63], off offset:3072 nt
	s_nop 0
	global_load_dwordx4 v[68:71], v[80:81], off nt
	global_load_dwordx4 v[72:75], v[80:81], off offset:1024 nt
	global_load_dwordx4 v[76:79], v[80:81], off offset:2048 nt
	global_load_dwordx4 v[86:89], v[80:81], off offset:3072 nt
	v_add_co_u32_e32 v80, vcc, s1, v66
	s_mov_b32 s1, 0x800000
	s_nop 0
	v_addc_co_u32_e32 v81, vcc, 0, v67, vcc
	global_load_dwordx4 v[90:93], v[80:81], off nt
	global_load_dwordx4 v[94:97], v[80:81], off offset:1024 nt
	global_load_dwordx4 v[98:101], v[80:81], off offset:2048 nt
	global_load_dwordx4 v[104:107], v[80:81], off offset:3072 nt
	s_mov_b64 s[18:19], 0x800000
	s_waitcnt vmcnt(11)
	v_pk_add_f32 v[36:37], v[36:37], v[48:49]
	v_pk_add_f32 v[34:35], v[34:35], v[46:47]
	s_waitcnt vmcnt(3)
	v_pk_add_f32 v[46:47], v[70:71], v[92:93]
	v_pk_add_f32 v[48:49], v[68:69], v[90:91]
	v_pk_add_f32 v[36:37], v[36:37], v[46:47]
	v_pk_add_f32 v[34:35], v[34:35], v[48:49]
	v_pk_add_f32 v[46:47], v[32:33], v[36:37]
	v_pk_add_f32 v[48:49], v[30:31], v[34:35]
	v_pk_add_f32 v[30:31], v[40:41], v[52:53]
	v_pk_add_f32 v[32:33], v[38:39], v[50:51]
	s_waitcnt vmcnt(2)
	v_pk_add_f32 v[34:35], v[74:75], v[96:97]
	v_pk_add_f32 v[36:37], v[72:73], v[94:95]
	v_pk_add_f32 v[30:31], v[30:31], v[34:35]
	v_pk_add_f32 v[32:33], v[32:33], v[36:37]
	v_pk_add_f32 v[50:51], v[28:29], v[30:31]
	v_pk_add_f32 v[52:53], v[26:27], v[32:33]
	v_pk_add_f32 v[26:27], v[44:45], v[56:57]
	v_pk_add_f32 v[28:29], v[42:43], v[54:55]
	s_waitcnt vmcnt(1)
	v_pk_add_f32 v[30:31], v[78:79], v[100:101]
	v_pk_add_f32 v[32:33], v[76:77], v[98:99]
	v_pk_add_f32 v[26:27], v[26:27], v[30:31]
	v_pk_add_f32 v[28:29], v[28:29], v[32:33]
	v_pk_add_f32 v[54:55], v[24:25], v[26:27]
	v_pk_add_f32 v[56:57], v[22:23], v[28:29]
	v_pk_add_f32 v[22:23], v[60:61], v[64:65]
	s_waitcnt vmcnt(0)
	v_pk_add_f32 v[26:27], v[88:89], v[106:107]
	v_pk_add_f32 v[24:25], v[58:59], v[62:63]
	v_pk_add_f32 v[22:23], v[22:23], v[26:27]
	v_pk_add_f32 v[28:29], v[86:87], v[104:105]
	v_pk_add_f32 v[58:59], v[20:21], v[22:23]
	v_add_co_u32_e32 v20, vcc, s1, v66
	s_mov_b32 s1, 0xa00000
	s_nop 0
	v_addc_co_u32_e32 v21, vcc, 0, v67, vcc
	v_add_co_u32_e32 v34, vcc, s1, v66
	s_mov_b32 s1, 0xc00000
	s_nop 0
	v_addc_co_u32_e32 v35, vcc, 0, v67, vcc
	v_add_co_u32_e32 v42, vcc, s1, v66
	s_mov_b32 s1, 0xe00000
	s_nop 0
	v_addc_co_u32_e32 v43, vcc, 0, v67, vcc
	v_pk_add_f32 v[24:25], v[24:25], v[28:29]
	v_add_co_u32_e32 v80, vcc, s1, v66
	v_pk_add_f32 v[60:61], v[18:19], v[24:25]
	v_lshl_add_u64 v[18:19], v[66:67], 0, s[18:19]
	v_addc_co_u32_e32 v81, vcc, 0, v67, vcc
	global_load_dwordx4 v[30:33], v[20:21], off nt
	global_load_dwordx4 v[26:29], v[18:19], off offset:1024 nt
	global_load_dwordx4 v[22:25], v[18:19], off offset:2048 nt
	s_nop 0
	global_load_dwordx4 v[18:21], v[18:19], off offset:3072 nt
	s_nop 0
	global_load_dwordx4 v[62:65], v[34:35], off nt
	global_load_dwordx4 v[68:71], v[34:35], off offset:1024 nt
	global_load_dwordx4 v[38:41], v[34:35], off offset:2048 nt
	s_nop 0
	global_load_dwordx4 v[34:37], v[34:35], off offset:3072 nt
	s_nop 0
	global_load_dwordx4 v[72:75], v[42:43], off nt
	global_load_dwordx4 v[76:79], v[42:43], off offset:1024 nt
	global_load_dwordx4 v[86:89], v[42:43], off offset:2048 nt
	s_nop 0
	global_load_dwordx4 v[42:45], v[42:43], off offset:3072 nt
	s_nop 0
	global_load_dwordx4 v[90:93], v[80:81], off nt
	global_load_dwordx4 v[94:97], v[80:81], off offset:1024 nt
	global_load_dwordx4 v[98:101], v[80:81], off offset:2048 nt
	global_load_dwordx4 v[104:107], v[80:81], off offset:3072 nt
	s_mov_b32 s1, 0x1000000
	s_mov_b64 s[18:19], 0x1000000
	s_waitcnt vmcnt(11)
	v_pk_add_f32 v[32:33], v[32:33], v[64:65]
	v_pk_add_f32 v[30:31], v[30:31], v[62:63]
	s_waitcnt vmcnt(3)
	v_pk_add_f32 v[62:63], v[74:75], v[92:93]
	v_pk_add_f32 v[20:21], v[20:21], v[36:37]
	v_pk_add_f32 v[18:19], v[18:19], v[34:35]
	s_waitcnt vmcnt(0)
; #define GAS __attribute__((address_space(1)))
;     ...
;         if (nparts > 0 && m >= ML) {
;             for (int p = 0; p < nparts; p += 4) {
;                 const GAS f32x4* pr = (const GAS f32x4*)(parts + (size_t)p * (512 * 1024) + (size_t)(m - ML) * DM) + F.lane;
;                 f32x4 w[4][4];
; #pragma unroll
;                 for (int q = 0; q < 4; ++q)
; #pragma unroll
;                     for (int j = 0; j < 4; ++j) w[q][j] = pr[(size_t)q * (512 * 1024 / 4) + 64 * j];
; #pragma unroll
;                 for (int j = 0; j < 4; ++j) v[j] += (w[0][j] + w[1][j]) + (w[2][j] + w[3][j]); }
;             GAS f32x4* cr = (GAS f32x4*)((float*)(F.ws + WS_CTXRES) + (size_t)(m - ML) * DM) + F.lane;
; #pragma unroll
;             for (int j = 0; j < 4; ++j) cr[64 * j] = v[j];
	v_pk_add_f32 v[34:35], v[44:45], v[106:107]
	v_pk_add_f32 v[36:37], v[42:43], v[104:105]
	v_pk_add_f32 v[20:21], v[20:21], v[34:35]
	v_pk_add_f32 v[34:35], v[18:19], v[36:37]
	v_pk_add_f32 v[64:65], v[72:73], v[90:91]
	v_pk_add_f32 v[18:19], v[58:59], v[20:21]
	v_pk_add_f32 v[20:21], v[60:61], v[34:35]
	v_add_co_u32_e32 v34, vcc, s1, v66
	v_pk_add_f32 v[32:33], v[32:33], v[62:63]
	v_pk_add_f32 v[62:63], v[30:31], v[64:65]
	v_addc_co_u32_e32 v35, vcc, 0, v67, vcc
	s_mov_b32 s1, 0x1200000
	v_pk_add_f32 v[30:31], v[46:47], v[32:33]
	v_pk_add_f32 v[32:33], v[48:49], v[62:63]
	v_add_co_u32_e32 v62, vcc, s1, v66
	v_pk_add_f32 v[28:29], v[28:29], v[70:71]
	v_pk_add_f32 v[26:27], v[26:27], v[68:69]
	v_pk_add_f32 v[46:47], v[78:79], v[96:97]
	v_pk_add_f32 v[48:49], v[76:77], v[94:95]
	v_addc_co_u32_e32 v63, vcc, 0, v67, vcc
	s_mov_b32 s1, 0x1400000
	v_pk_add_f32 v[28:29], v[28:29], v[46:47]
	v_pk_add_f32 v[46:47], v[26:27], v[48:49]
	v_pk_add_f32 v[24:25], v[24:25], v[40:41]
	v_pk_add_f32 v[22:23], v[22:23], v[38:39]
	v_pk_add_f32 v[38:39], v[88:89], v[100:101]
	v_pk_add_f32 v[40:41], v[86:87], v[98:99]
	v_add_co_u32_e32 v80, vcc, s1, v66
	v_pk_add_f32 v[26:27], v[50:51], v[28:29]
	v_pk_add_f32 v[28:29], v[52:53], v[46:47]
	v_pk_add_f32 v[24:25], v[24:25], v[38:39]
	v_pk_add_f32 v[38:39], v[22:23], v[40:41]
	v_lshl_add_u64 v[46:47], v[66:67], 0, s[18:19]
	v_addc_co_u32_e32 v81, vcc, 0, v67, vcc
	s_mov_b32 s1, 0x1600000
	v_pk_add_f32 v[22:23], v[54:55], v[24:25]
	v_pk_add_f32 v[24:25], v[56:57], v[38:39]
	global_load_dwordx4 v[34:37], v[34:35], off nt
	s_nop 0
	global_load_dwordx4 v[38:41], v[46:47], off offset:1024 nt
	global_load_dwordx4 v[42:45], v[46:47], off offset:2048 nt
	s_nop 0
	global_load_dwordx4 v[46:49], v[46:47], off offset:3072 nt
	s_nop 0
	global_load_dwordx4 v[50:53], v[62:63], off nt
	global_load_dwordx4 v[54:57], v[62:63], off offset:1024 nt
	global_load_dwordx4 v[58:61], v[62:63], off offset:2048 nt
	s_nop 0
	global_load_dwordx4 v[62:65], v[62:63], off offset:3072 nt
	s_nop 0
	global_load_dwordx4 v[68:71], v[80:81], off nt
	global_load_dwordx4 v[72:75], v[80:81], off offset:1024 nt
	global_load_dwordx4 v[76:79], v[80:81], off offset:2048 nt
	global_load_dwordx4 v[86:89], v[80:81], off offset:3072 nt
	v_add_co_u32_e32 v80, vcc, s1, v66
	s_mov_b32 s1, 0x1800000
	s_nop 0
	v_addc_co_u32_e32 v81, vcc, 0, v67, vcc
	global_load_dwordx4 v[90:93], v[80:81], off nt
	global_load_dwordx4 v[94:97], v[80:81], off offset:1024 nt
	global_load_dwordx4 v[104:107], v[80:81], off offset:2048 nt
	global_load_dwordx4 v[108:111], v[80:81], off offset:3072 nt
	s_mov_b64 s[18:19], 0x1800000
	s_waitcnt vmcnt(11)
	v_pk_add_f32 v[36:37], v[36:37], v[52:53]
	v_pk_add_f32 v[34:35], v[34:35], v[50:51]
	s_waitcnt vmcnt(3)
	v_pk_add_f32 v[50:51], v[70:71], v[92:93]
	v_pk_add_f32 v[52:53], v[68:69], v[90:91]
	v_pk_add_f32 v[36:37], v[36:37], v[50:51]
	v_pk_add_f32 v[34:35], v[34:35], v[52:53]
	v_pk_add_f32 v[98:99], v[30:31], v[36:37]
	v_pk_add_f32 v[100:101], v[32:33], v[34:35]
	v_pk_add_f32 v[32:33], v[38:39], v[54:55]
	s_waitcnt vmcnt(2)
	v_pk_add_f32 v[36:37], v[72:73], v[94:95]
	v_pk_add_f32 v[30:31], v[40:41], v[56:57]
	v_pk_add_f32 v[32:33], v[32:33], v[36:37]
	v_pk_add_f32 v[34:35], v[74:75], v[96:97]
	v_pk_add_f32 v[96:97], v[28:29], v[32:33]
	v_pk_add_f32 v[28:29], v[42:43], v[58:59]
	s_waitcnt vmcnt(1)
	v_pk_add_f32 v[32:33], v[76:77], v[104:105]
	v_pk_add_f32 v[30:31], v[30:31], v[34:35]
	v_pk_add_f32 v[28:29], v[28:29], v[32:33]
	v_pk_add_f32 v[94:95], v[26:27], v[30:31]
	v_pk_add_f32 v[26:27], v[44:45], v[60:61]
	v_pk_add_f32 v[30:31], v[78:79], v[106:107]
	v_pk_add_f32 v[92:93], v[24:25], v[28:29]
	v_pk_add_f32 v[24:25], v[46:47], v[62:63]
	s_waitcnt vmcnt(0)
; #define GAS __attribute__((address_space(1)))
;     ...
;         if (nparts > 0 && m >= ML) {
;             for (int p = 0; p < nparts; p += 4) {
;                 const GAS f32x4* pr = (const GAS f32x4*)(parts + (size_t)p * (512 * 1024) + (size_t)(m - ML) * DM) + F.lane;
;                 f32x4 w[4][4];
; #pragma unroll
;                 for (int q = 0; q < 4; ++q)
; #pragma unroll
;                     for (int j = 0; j < 4; ++j) w[q][j] = pr[(size_t)q * (512 * 1024 / 4) + 64 * j];
; #pragma unroll
;                 for (int j = 0; j < 4; ++j) v[j] += (w[0][j] + w[1][j]) + (w[2][j] + w[3][j]); }
;             GAS f32x4* cr = (GAS f32x4*)((float*)(F.ws + WS_CTXRES) + (size_t)(m - ML) * DM) + F.lane;
; #pragma unroll
;             for (int j = 0; j < 4; ++j) cr[64 * j] = v[j];
	v_pk_add_f32 v[28:29], v[86:87], v[108:109]
	v_pk_add_f32 v[26:27], v[26:27], v[30:31]
	v_pk_add_f32 v[24:25], v[24:25], v[28:29]
	v_pk_add_f32 v[90:91], v[22:23], v[26:27]
	v_pk_add_f32 v[26:27], v[88:89], v[110:111]
	v_pk_add_f32 v[88:89], v[20:21], v[24:25]
	v_add_co_u32_e32 v20, vcc, s1, v66
	s_mov_b32 s1, 0x1a00000
	s_nop 0
	v_addc_co_u32_e32 v21, vcc, 0, v67, vcc
	v_add_co_u32_e32 v34, vcc, s1, v66
	s_mov_b32 s1, 0x1c00000
	s_nop 0
	v_addc_co_u32_e32 v35, vcc, 0, v67, vcc
	v_add_co_u32_e32 v42, vcc, s1, v66
	v_pk_add_f32 v[22:23], v[48:49], v[64:65]
	s_nop 0
	v_addc_co_u32_e32 v43, vcc, 0, v67, vcc
	s_mov_b32 s1, 0x1e00000
	v_pk_add_f32 v[22:23], v[22:23], v[26:27]
	v_add_co_u32_e32 v78, vcc, s1, v66
	v_pk_add_f32 v[86:87], v[18:19], v[22:23]
	v_lshl_add_u64 v[18:19], v[66:67], 0, s[18:19]
	v_addc_co_u32_e32 v79, vcc, 0, v67, vcc
	global_load_dwordx4 v[30:33], v[20:21], off nt
	global_load_dwordx4 v[26:29], v[18:19], off offset:1024 nt
	global_load_dwordx4 v[22:25], v[18:19], off offset:2048 nt
	s_nop 0
	global_load_dwordx4 v[18:21], v[18:19], off offset:3072 nt
	s_nop 0
	global_load_dwordx4 v[54:57], v[34:35], off nt
	global_load_dwordx4 v[46:49], v[34:35], off offset:1024 nt
	global_load_dwordx4 v[38:41], v[34:35], off offset:2048 nt
	s_nop 0
	global_load_dwordx4 v[34:37], v[34:35], off offset:3072 nt
	s_nop 0
	global_load_dwordx4 v[62:65], v[42:43], off nt
	global_load_dwordx4 v[58:61], v[42:43], off offset:1024 nt
	global_load_dwordx4 v[50:53], v[42:43], off offset:2048 nt
	s_nop 0
	global_load_dwordx4 v[42:45], v[42:43], off offset:3072 nt
	s_nop 0
	global_load_dwordx4 v[66:69], v[78:79], off nt
	global_load_dwordx4 v[70:73], v[78:79], off offset:1024 nt
	global_load_dwordx4 v[74:77], v[78:79], off offset:2048 nt
	s_nop 0
	global_load_dwordx4 v[78:81], v[78:79], off offset:3072 nt
	s_waitcnt vmcnt(11)
	v_pk_add_f32 v[32:33], v[32:33], v[56:57]
	v_pk_add_f32 v[30:31], v[30:31], v[54:55]
	s_waitcnt vmcnt(3)
	v_pk_add_f32 v[54:55], v[64:65], v[68:69]
	v_pk_add_f32 v[56:57], v[62:63], v[66:67]
	v_pk_add_f32 v[28:29], v[28:29], v[48:49]
	v_pk_add_f32 v[26:27], v[26:27], v[46:47]
	s_waitcnt vmcnt(2)
	v_pk_add_f32 v[46:47], v[60:61], v[72:73]
	v_pk_add_f32 v[48:49], v[58:59], v[70:71]
	v_pk_add_f32 v[24:25], v[24:25], v[40:41]
	v_pk_add_f32 v[22:23], v[22:23], v[38:39]
	s_waitcnt vmcnt(1)
	v_pk_add_f32 v[38:39], v[52:53], v[76:77]
	v_pk_add_f32 v[40:41], v[50:51], v[74:75]
	v_pk_add_f32 v[20:21], v[20:21], v[36:37]
	v_pk_add_f32 v[18:19], v[18:19], v[34:35]
	s_waitcnt vmcnt(0)
	v_pk_add_f32 v[34:35], v[44:45], v[80:81]
	v_pk_add_f32 v[36:37], v[42:43], v[78:79]
	v_pk_add_f32 v[32:33], v[32:33], v[54:55]
	v_pk_add_f32 v[30:31], v[30:31], v[56:57]
	v_pk_add_f32 v[28:29], v[28:29], v[46:47]
	v_pk_add_f32 v[26:27], v[26:27], v[48:49]
	v_pk_add_f32 v[24:25], v[24:25], v[38:39]
	v_pk_add_f32 v[22:23], v[22:23], v[40:41]
	v_pk_add_f32 v[20:21], v[20:21], v[34:35]
	v_pk_add_f32 v[18:19], v[18:19], v[36:37]
	v_pk_add_f32 v[32:33], v[98:99], v[32:33]
	v_pk_add_f32 v[30:31], v[100:101], v[30:31]
	v_pk_add_f32 v[28:29], v[94:95], v[28:29]
	v_pk_add_f32 v[26:27], v[96:97], v[26:27]
	v_pk_add_f32 v[24:25], v[90:91], v[24:25]
	v_pk_add_f32 v[22:23], v[92:93], v[22:23]
	v_pk_add_f32 v[20:21], v[86:87], v[20:21]
	v_pk_add_f32 v[18:19], v[88:89], v[18:19]
	v_lshl_add_u64 v[34:35], v[82:83], 0, s[14:15]
	global_store_dwordx4 v[34:35], v[30:33], off
	global_store_dwordx4 v[34:35], v[26:29], off offset:1024
	global_store_dwordx4 v[34:35], v[22:25], off offset:2048
	global_store_dwordx4 v[34:35], v[18:21], off offset:3072
	s_branch .LBB0_160
